# stack3 + B_MIX v-row loads batched + gain-folding convert_T passes batched
# baseline (speedup 1.0000x reference)
.LBB0_149:
	s_or_b64 exec, exec, s[0:1]
	s_lshl_b32 s0, s14, 7
	v_add_u32_e32 v22, s0, v82
	s_lshl_b32 s1, s13, 8
	v_ashrrev_i32_e32 v23, 31, v22
	v_readlane_b32 s14, v251, 9
	v_or_b32_e32 v0, s1, v81
	v_lshlrev_b64 v[2:3], 13, v[22:23]
	v_readlane_b32 s15, v251, 10
	v_lshlrev_b32_e32 v10, 2, v0
	v_lshlrev_b32_e32 v0, 1, v0
	v_lshl_add_u64 v[2:3], s[14:15], 0, v[2:3]
	v_lshl_add_u64 v[18:19], v[2:3], 0, v[0:1]
	s_movk_i32 s16, 0x1000
	v_readlane_b32 s52, v249, 13
	v_add_co_u32_e32 v18, vcc, s16, v18
	v_readlane_b32 s60, v249, 21
	v_readlane_b32 s61, v249, 22
	v_readlane_b32 s62, v249, 23
	v_readlane_b32 s63, v249, 24
	v_addc_co_u32_e32 v19, vcc, 0, v19, vcc
	s_waitcnt lgkmcnt(0)
	s_barrier
	global_load_dwordx4 v[6:9], v10, s[60:61]
	s_nop 0
	global_load_dwordx4 v[14:17], v10, s[62:63]
	global_load_dwordx4 v[2:5], v10, s[60:61] offset:16
	s_nop 0
	global_load_dwordx4 v[10:13], v10, s[62:63] offset:16
	s_add_i32 s2, 0, 0x1a800
	global_load_dwordx4 v[30:33], v[18:19], off
	v_mov_b32_e32 v228, 0x20000
	v_mov_b32_e32 v229, 0
	v_lshl_add_u64 v[230:231], v[18:19], 0, v[228:229]
	v_lshl_add_u64 v[230:231], v[230:231], 0, v[228:229]
	global_load_dwordx4 v[200:203], v[230:231], off
	v_lshl_add_u64 v[230:231], v[230:231], 0, v[228:229]
	global_load_dwordx4 v[204:207], v[230:231], off
	v_lshl_add_u64 v[230:231], v[230:231], 0, v[228:229]
	global_load_dwordx4 v[208:211], v[230:231], off
	v_lshl_add_u64 v[230:231], v[230:231], 0, v[228:229]
	global_load_dwordx4 v[212:215], v[230:231], off
	v_lshl_add_u64 v[230:231], v[230:231], 0, v[228:229]
	global_load_dwordx4 v[216:219], v[230:231], off
	v_lshl_add_u64 v[230:231], v[230:231], 0, v[228:229]
	global_load_dwordx4 v[220:223], v[230:231], off
	v_add_u32_e32 v19, s2, v83
	v_add_u32_e32 v18, 16, v22
	ds_read_b64 v[38:39], v19
	v_ashrrev_i32_e32 v19, 31, v18
	v_lshlrev_b64 v[18:19], 13, v[18:19]
	v_lshl_add_u64 v[18:19], s[14:15], 0, v[18:19]
	v_lshl_add_u64 v[18:19], v[18:19], 0, v[0:1]
	v_add_co_u32_e32 v18, vcc, s16, v18
	v_add_u32_e32 v20, 32, v22
	s_nop 0
	v_addc_co_u32_e32 v19, vcc, 0, v19, vcc
	global_load_dwordx4 v[34:37], v[18:19], off
	v_add_u32_e32 v24, 48, v22
	v_ashrrev_i32_e32 v21, 31, v20
	v_ashrrev_i32_e32 v25, 31, v24
	v_add_u32_e32 v26, 64, v22
	v_add_u32_e32 v28, 0x50, v22
	v_lshlrev_b64 v[18:19], 13, v[20:21]
	v_lshlrev_b64 v[20:21], 13, v[24:25]
	v_ashrrev_i32_e32 v27, 31, v26
	v_ashrrev_i32_e32 v29, 31, v28
	v_lshl_add_u64 v[18:19], s[14:15], 0, v[18:19]
	v_lshl_add_u64 v[20:21], s[14:15], 0, v[20:21]
	v_lshlrev_b64 v[24:25], 13, v[26:27]
	v_lshlrev_b64 v[26:27], 13, v[28:29]
	v_lshl_add_u64 v[42:43], v[18:19], 0, v[0:1]
	v_lshl_add_u64 v[28:29], v[20:21], 0, v[0:1]
	v_lshl_add_u64 v[24:25], s[14:15], 0, v[24:25]
	v_lshl_add_u64 v[40:41], s[14:15], 0, v[26:27]
	v_lshl_add_u64 v[26:27], v[24:25], 0, v[0:1]
	v_lshl_add_u64 v[24:25], v[40:41], 0, v[0:1]
	s_mov_b32 s3, 0xffff0000
	v_readlane_b32 s53, v249, 14
	v_readlane_b32 s54, v249, 15
	v_readlane_b32 s55, v249, 16
	v_readlane_b32 s56, v249, 17
	v_readlane_b32 s57, v249, 18
	v_readlane_b32 s58, v249, 19
	v_readlane_b32 s59, v249, 20
	v_readlane_b32 s64, v249, 25
	v_readlane_b32 s65, v249, 26
	v_readlane_b32 s66, v249, 27
	v_readlane_b32 s67, v249, 28
	s_waitcnt vmcnt(0)
	v_mov_b32_e32 v18, v6
	v_mov_b32_e32 v19, v8
	s_waitcnt vmcnt(4)
	v_mov_b32_e32 v20, v14
	v_mov_b32_e32 v21, v16
	v_mov_b32_e32 v8, v7
	v_mov_b32_e32 v16, v15
	s_waitcnt vmcnt(3)
	v_mov_b32_e32 v6, v2
	v_mov_b32_e32 v7, v4
	s_waitcnt vmcnt(2)
	v_mov_b32_e32 v14, v10
	v_mov_b32_e32 v15, v12
	v_mov_b32_e32 v4, v3
	v_mov_b32_e32 v12, v11
	s_waitcnt vmcnt(1)
	v_lshlrev_b32_e32 v3, 16, v31
	v_lshlrev_b32_e32 v2, 16, v30
	v_and_b32_e32 v11, 0xffff0000, v31
	v_and_b32_e32 v10, 0xffff0000, v30
	v_lshlrev_b32_e32 v31, 16, v33
	v_lshlrev_b32_e32 v30, 16, v32
	v_and_b32_e32 v33, 0xffff0000, v33
	v_and_b32_e32 v32, 0xffff0000, v32
	s_waitcnt lgkmcnt(0)
	v_pk_add_f32 v[30:31], v[30:31], v[38:39] op_sel_hi:[1,0] neg_lo:[0,1] neg_hi:[0,1]
	v_pk_add_f32 v[2:3], v[2:3], v[38:39] op_sel_hi:[1,0] neg_lo:[0,1] neg_hi:[0,1]
	v_pk_add_f32 v[10:11], v[10:11], v[38:39] op_sel_hi:[1,0] neg_lo:[0,1] neg_hi:[0,1]
	v_pk_add_f32 v[32:33], v[32:33], v[38:39] op_sel_hi:[1,0] neg_lo:[0,1] neg_hi:[0,1]
	v_pk_mul_f32 v[30:31], v[30:31], v[38:39] op_sel:[0,1]
	v_pk_mul_f32 v[2:3], v[2:3], v[38:39] op_sel:[0,1]
	v_pk_mul_f32 v[10:11], v[10:11], v[38:39] op_sel:[0,1]
	v_pk_mul_f32 v[32:33], v[32:33], v[38:39] op_sel:[0,1]
	v_pk_fma_f32 v[38:39], v[6:7], v[30:31], v[14:15]
	v_add_co_u32_e32 v30, vcc, s16, v42
	v_pk_fma_f32 v[40:41], v[4:5], v[32:33], v[12:13]
	s_nop 0
	v_addc_co_u32_e32 v31, vcc, 0, v43, vcc
	v_mov_b64_e32 v[30:31], v[200:201]
	v_mov_b64_e32 v[32:33], v[202:203]
	v_pk_fma_f32 v[2:3], v[18:19], v[2:3], v[20:21]
	v_bfe_u32 v23, v41, 16, 1
	v_bfe_u32 v44, v40, 16, 1
	v_pk_fma_f32 v[10:11], v[8:9], v[10:11], v[16:17]
	v_add3_u32 v40, v40, v44, s87
	v_add3_u32 v23, v41, v23, s87
	v_bfe_u32 v41, v2, 16, 1
	v_bfe_u32 v42, v3, 16, 1
	v_bfe_u32 v43, v38, 16, 1
	v_bfe_u32 v44, v39, 16, 1
	v_bfe_u32 v45, v11, 16, 1
	v_bfe_u32 v46, v10, 16, 1
	v_add3_u32 v39, v39, v44, s87
	v_add3_u32 v38, v38, v43, s87
	v_add3_u32 v3, v3, v42, s87
	v_add3_u32 v2, v2, v41, s87
	v_add3_u32 v10, v10, v46, s87
	v_add3_u32 v11, v11, v45, s87
	v_lshrrev_b32_e32 v2, 16, v2
	v_lshrrev_b32_e32 v3, 16, v3
	v_lshrrev_b32_e32 v38, 16, v38
	v_lshrrev_b32_e32 v39, 16, v39
	v_and_or_b32 v41, v23, s3, v39
	v_and_or_b32 v40, v40, s3, v38
	v_and_or_b32 v39, v11, s3, v3
	v_and_or_b32 v38, v10, s3, v2
	ds_write_b128 v96, v[38:41]
	v_add_u32_e32 v2, s2, v84
	ds_read_b64 v[2:3], v2
	s_waitcnt vmcnt(1)
	v_lshlrev_b32_e32 v39, 16, v35
	v_lshlrev_b32_e32 v38, 16, v34
	v_and_b32_e32 v35, 0xffff0000, v35
	v_and_b32_e32 v34, 0xffff0000, v34
	s_waitcnt lgkmcnt(0)
	v_pk_add_f32 v[34:35], v[34:35], v[2:3] op_sel_hi:[1,0] neg_lo:[0,1] neg_hi:[0,1]
	v_add_co_u32_e32 v28, vcc, s16, v28
	v_pk_mul_f32 v[34:35], v[34:35], v[2:3] op_sel:[0,1]
	v_pk_add_f32 v[38:39], v[38:39], v[2:3] op_sel_hi:[1,0] neg_lo:[0,1] neg_hi:[0,1]
	v_pk_fma_f32 v[40:41], v[8:9], v[34:35], v[16:17]
	v_lshlrev_b32_e32 v35, 16, v37
	v_lshlrev_b32_e32 v34, 16, v36
	v_pk_add_f32 v[34:35], v[34:35], v[2:3] op_sel_hi:[1,0] neg_lo:[0,1] neg_hi:[0,1]
	v_addc_co_u32_e32 v29, vcc, 0, v29, vcc
	v_pk_mul_f32 v[34:35], v[34:35], v[2:3] op_sel:[0,1]
	v_pk_mul_f32 v[38:39], v[38:39], v[2:3] op_sel:[0,1]
	v_pk_fma_f32 v[42:43], v[6:7], v[34:35], v[14:15]
	v_and_b32_e32 v35, 0xffff0000, v37
	v_and_b32_e32 v34, 0xffff0000, v36
	v_pk_add_f32 v[34:35], v[34:35], v[2:3] op_sel_hi:[1,0] neg_lo:[0,1] neg_hi:[0,1]
	v_pk_fma_f32 v[38:39], v[18:19], v[38:39], v[20:21]
	v_pk_mul_f32 v[2:3], v[34:35], v[2:3] op_sel:[0,1]
	v_mov_b64_e32 v[34:35], v[204:205]
	v_mov_b64_e32 v[36:37], v[206:207]
	v_pk_fma_f32 v[2:3], v[4:5], v[2:3], v[12:13]
	v_bfe_u32 v45, v41, 16, 1
	v_bfe_u32 v23, v3, 16, 1
	v_bfe_u32 v44, v2, 16, 1
	v_bfe_u32 v46, v40, 16, 1
	v_add3_u32 v28, v40, v46, s87
	v_add3_u32 v29, v41, v45, s87
	v_add3_u32 v2, v2, v44, s87
	v_add3_u32 v3, v3, v23, s87
	v_bfe_u32 v23, v38, 16, 1
	v_bfe_u32 v40, v39, 16, 1
	v_bfe_u32 v41, v42, 16, 1
	v_bfe_u32 v44, v43, 16, 1
	v_add3_u32 v43, v43, v44, s87
	v_add3_u32 v41, v42, v41, s87
	v_add3_u32 v39, v39, v40, s87
	v_add3_u32 v23, v38, v23, s87
	v_lshrrev_b32_e32 v23, 16, v23
	v_lshrrev_b32_e32 v38, 16, v39
	v_lshrrev_b32_e32 v39, 16, v41
	v_lshrrev_b32_e32 v40, 16, v43
	v_and_or_b32 v41, v3, s3, v40
	v_and_or_b32 v40, v2, s3, v39
	v_and_or_b32 v39, v29, s3, v38
	v_and_or_b32 v38, v28, s3, v23
	ds_write_b128 v96, v[38:41] offset:9216
	v_add_u32_e32 v2, s2, v85
	ds_read_b64 v[2:3], v2
	s_waitcnt vmcnt(1)
	v_lshlrev_b32_e32 v29, 16, v31
	v_lshlrev_b32_e32 v28, 16, v30
	v_add_co_u32_e32 v26, vcc, s16, v26
	s_waitcnt lgkmcnt(0)
	v_pk_add_f32 v[28:29], v[28:29], v[2:3] op_sel_hi:[1,0] neg_lo:[0,1] neg_hi:[0,1]
	v_addc_co_u32_e32 v27, vcc, 0, v27, vcc
	v_pk_mul_f32 v[28:29], v[28:29], v[2:3] op_sel:[0,1]
	v_add_u32_e32 v10, 0x60, v22
	v_pk_fma_f32 v[38:39], v[18:19], v[28:29], v[20:21]
	v_and_b32_e32 v29, 0xffff0000, v31
	v_and_b32_e32 v28, 0xffff0000, v30
	v_pk_add_f32 v[28:29], v[28:29], v[2:3] op_sel_hi:[1,0] neg_lo:[0,1] neg_hi:[0,1]
	v_ashrrev_i32_e32 v11, 31, v10
	v_pk_mul_f32 v[28:29], v[28:29], v[2:3] op_sel:[0,1]
	v_lshlrev_b64 v[10:11], 13, v[10:11]
	v_pk_fma_f32 v[30:31], v[8:9], v[28:29], v[16:17]
	v_lshlrev_b32_e32 v29, 16, v33
	v_lshlrev_b32_e32 v28, 16, v32
	v_pk_add_f32 v[28:29], v[28:29], v[2:3] op_sel_hi:[1,0] neg_lo:[0,1] neg_hi:[0,1]
	v_bfe_u32 v42, v30, 16, 1
	v_pk_mul_f32 v[28:29], v[28:29], v[2:3] op_sel:[0,1]
	v_add3_u32 v30, v30, v42, s87
	v_pk_fma_f32 v[40:41], v[6:7], v[28:29], v[14:15]
	v_and_b32_e32 v29, 0xffff0000, v33
	v_and_b32_e32 v28, 0xffff0000, v32
	v_pk_add_f32 v[28:29], v[28:29], v[2:3] op_sel_hi:[1,0] neg_lo:[0,1] neg_hi:[0,1]
	v_bfe_u32 v33, v31, 16, 1
	v_pk_mul_f32 v[2:3], v[28:29], v[2:3] op_sel:[0,1]
	v_add3_u32 v31, v31, v33, s87
	v_pk_fma_f32 v[2:3], v[4:5], v[2:3], v[12:13]
	v_bfe_u32 v33, v40, 16, 1
	v_bfe_u32 v23, v3, 16, 1
	v_bfe_u32 v32, v2, 16, 1
	v_add3_u32 v2, v2, v32, s87
	v_add3_u32 v3, v3, v23, s87
	v_bfe_u32 v23, v38, 16, 1
	v_bfe_u32 v32, v39, 16, 1
	v_bfe_u32 v42, v41, 16, 1
	v_add3_u32 v41, v41, v42, s87
	v_add3_u32 v33, v40, v33, s87
	v_add3_u32 v32, v39, v32, s87
	v_add3_u32 v23, v38, v23, s87
	v_mov_b64_e32 v[26:27], v[208:209]
	v_mov_b64_e32 v[28:29], v[210:211]
	v_lshrrev_b32_e32 v23, 16, v23
	v_lshrrev_b32_e32 v38, 16, v32
	v_lshrrev_b32_e32 v32, 16, v33
	v_lshrrev_b32_e32 v33, 16, v41
	v_and_or_b32 v33, v3, s3, v33
	v_and_or_b32 v32, v2, s3, v32
	v_and_or_b32 v31, v31, s3, v38
	v_and_or_b32 v30, v30, s3, v23
	ds_write_b128 v96, v[30:33] offset:18432
	v_add_u32_e32 v2, s2, v86
	ds_read_b64 v[2:3], v2
	v_add_u32_e32 v38, 0x70, v22
	s_waitcnt vmcnt(1)
	v_lshlrev_b32_e32 v23, 16, v35
	v_lshlrev_b32_e32 v22, 16, v34
	v_lshl_add_u64 v[10:11], s[14:15], 0, v[10:11]
	s_waitcnt lgkmcnt(0)
	v_pk_add_f32 v[22:23], v[22:23], v[2:3] op_sel_hi:[1,0] neg_lo:[0,1] neg_hi:[0,1]
	v_lshl_add_u64 v[10:11], v[10:11], 0, v[0:1]
	v_pk_mul_f32 v[22:23], v[22:23], v[2:3] op_sel:[0,1]
	s_nop 0
	v_pk_fma_f32 v[30:31], v[18:19], v[22:23], v[20:21]
	v_and_b32_e32 v23, 0xffff0000, v35
	v_and_b32_e32 v22, 0xffff0000, v34
	v_pk_add_f32 v[22:23], v[22:23], v[2:3] op_sel_hi:[1,0] neg_lo:[0,1] neg_hi:[0,1]
	s_nop 0
	v_pk_mul_f32 v[22:23], v[22:23], v[2:3] op_sel:[0,1]
	s_nop 0
	v_pk_fma_f32 v[32:33], v[8:9], v[22:23], v[16:17]
	v_lshlrev_b32_e32 v23, 16, v37
	v_lshlrev_b32_e32 v22, 16, v36
	v_pk_add_f32 v[22:23], v[22:23], v[2:3] op_sel_hi:[1,0] neg_lo:[0,1] neg_hi:[0,1]
	v_bfe_u32 v39, v33, 16, 1
	v_pk_mul_f32 v[22:23], v[22:23], v[2:3] op_sel:[0,1]
	v_bfe_u32 v40, v32, 16, 1
	v_pk_fma_f32 v[34:35], v[6:7], v[22:23], v[14:15]
	v_and_b32_e32 v23, 0xffff0000, v37
	v_and_b32_e32 v22, 0xffff0000, v36
	v_pk_add_f32 v[22:23], v[22:23], v[2:3] op_sel_hi:[1,0] neg_lo:[0,1] neg_hi:[0,1]
	v_add3_u32 v40, v32, v40, s87
	v_pk_mul_f32 v[2:3], v[22:23], v[2:3] op_sel:[0,1]
	v_add_co_u32_e32 v22, vcc, s16, v24
	v_pk_fma_f32 v[2:3], v[4:5], v[2:3], v[12:13]
	s_nop 0
	v_addc_co_u32_e32 v23, vcc, 0, v25, vcc
	v_mov_b64_e32 v[22:23], v[212:213]
	v_mov_b64_e32 v[24:25], v[214:215]
	v_bfe_u32 v36, v3, 16, 1
	v_bfe_u32 v37, v2, 16, 1
	v_add3_u32 v39, v33, v39, s87
	v_add3_u32 v2, v2, v37, s87
	v_add3_u32 v3, v3, v36, s87
	v_bfe_u32 v32, v30, 16, 1
	v_bfe_u32 v33, v31, 16, 1
	v_bfe_u32 v36, v34, 16, 1
	v_bfe_u32 v37, v35, 16, 1
	v_add3_u32 v35, v35, v37, s87
	v_add3_u32 v34, v34, v36, s87
	v_add3_u32 v31, v31, v33, s87
	v_add3_u32 v30, v30, v32, s87
	v_lshrrev_b32_e32 v30, 16, v30
	v_lshrrev_b32_e32 v31, 16, v31
	v_lshrrev_b32_e32 v32, 16, v34
	v_lshrrev_b32_e32 v33, 16, v35
	v_and_or_b32 v33, v3, s3, v33
	v_and_or_b32 v32, v2, s3, v32
	v_and_or_b32 v31, v39, s3, v31
	v_and_or_b32 v30, v40, s3, v30
	ds_write_b128 v96, v[30:33] offset:27648
	v_add_u32_e32 v2, s2, v87
	ds_read_b64 v[2:3], v2
	v_ashrrev_i32_e32 v39, 31, v38
	v_add_co_u32_e32 v10, vcc, s16, v10
	v_lshlrev_b64 v[34:35], 13, v[38:39]
	s_nop 0
	v_addc_co_u32_e32 v11, vcc, 0, v11, vcc
	s_waitcnt vmcnt(1)
	v_lshlrev_b32_e32 v31, 16, v27
	v_lshlrev_b32_e32 v30, 16, v26
	v_and_b32_e32 v27, 0xffff0000, v27
	v_and_b32_e32 v26, 0xffff0000, v26
	s_waitcnt lgkmcnt(0)
	v_pk_add_f32 v[26:27], v[26:27], v[2:3] op_sel_hi:[1,0] neg_lo:[0,1] neg_hi:[0,1]
	v_pk_add_f32 v[30:31], v[30:31], v[2:3] op_sel_hi:[1,0] neg_lo:[0,1] neg_hi:[0,1]
	v_pk_mul_f32 v[26:27], v[26:27], v[2:3] op_sel:[0,1]
	v_pk_mul_f32 v[30:31], v[30:31], v[2:3] op_sel:[0,1]
	v_pk_fma_f32 v[32:33], v[8:9], v[26:27], v[16:17]
	v_lshlrev_b32_e32 v27, 16, v29
	v_lshlrev_b32_e32 v26, 16, v28
	v_pk_add_f32 v[26:27], v[26:27], v[2:3] op_sel_hi:[1,0] neg_lo:[0,1] neg_hi:[0,1]
	v_pk_fma_f32 v[30:31], v[18:19], v[30:31], v[20:21]
	v_pk_mul_f32 v[26:27], v[26:27], v[2:3] op_sel:[0,1]
	v_bfe_u32 v40, v33, 16, 1
	v_pk_fma_f32 v[36:37], v[6:7], v[26:27], v[14:15]
	v_and_b32_e32 v27, 0xffff0000, v29
	v_and_b32_e32 v26, 0xffff0000, v28
	v_pk_add_f32 v[26:27], v[26:27], v[2:3] op_sel_hi:[1,0] neg_lo:[0,1] neg_hi:[0,1]
	v_bfe_u32 v41, v32, 16, 1
	v_pk_mul_f32 v[2:3], v[26:27], v[2:3] op_sel:[0,1]
	v_mov_b64_e32 v[26:27], v[216:217]
	v_mov_b64_e32 v[28:29], v[218:219]
	v_pk_fma_f32 v[2:3], v[4:5], v[2:3], v[12:13]
	v_add3_u32 v10, v32, v41, s87
	v_bfe_u32 v38, v3, 16, 1
	v_bfe_u32 v39, v2, 16, 1
	v_add3_u32 v11, v33, v40, s87
	v_add3_u32 v2, v2, v39, s87
	v_add3_u32 v3, v3, v38, s87
	v_bfe_u32 v32, v30, 16, 1
	v_bfe_u32 v33, v31, 16, 1
	v_bfe_u32 v38, v36, 16, 1
	v_bfe_u32 v39, v37, 16, 1
	v_add3_u32 v37, v37, v39, s87
	v_add3_u32 v36, v36, v38, s87
	v_add3_u32 v31, v31, v33, s87
	v_add3_u32 v30, v30, v32, s87
	v_lshrrev_b32_e32 v30, 16, v30
	v_lshrrev_b32_e32 v31, 16, v31
	v_lshrrev_b32_e32 v32, 16, v36
	v_lshrrev_b32_e32 v33, 16, v37
	v_and_or_b32 v33, v3, s3, v33
	v_and_or_b32 v32, v2, s3, v32
	v_and_or_b32 v31, v11, s3, v31
	v_and_or_b32 v30, v10, s3, v30
	ds_write_b128 v96, v[30:33] offset:36864
	v_add_u32_e32 v2, s2, v88
	ds_read_b64 v[2:3], v2
	s_waitcnt vmcnt(1)
	v_lshlrev_b32_e32 v31, 16, v23
	v_lshlrev_b32_e32 v30, 16, v22
	v_and_b32_e32 v23, 0xffff0000, v23
	v_and_b32_e32 v22, 0xffff0000, v22
	s_waitcnt lgkmcnt(0)
	v_pk_add_f32 v[22:23], v[22:23], v[2:3] op_sel_hi:[1,0] neg_lo:[0,1] neg_hi:[0,1]
	v_lshl_add_u64 v[10:11], s[14:15], 0, v[34:35]
	v_pk_mul_f32 v[22:23], v[22:23], v[2:3] op_sel:[0,1]
	v_lshl_add_u64 v[10:11], v[10:11], 0, v[0:1]
	v_pk_fma_f32 v[32:33], v[8:9], v[22:23], v[16:17]
	v_lshlrev_b32_e32 v23, 16, v25
	v_lshlrev_b32_e32 v22, 16, v24
	v_pk_add_f32 v[22:23], v[22:23], v[2:3] op_sel_hi:[1,0] neg_lo:[0,1] neg_hi:[0,1]
	v_add_co_u32_e32 v10, vcc, s16, v10
	v_pk_mul_f32 v[22:23], v[22:23], v[2:3] op_sel:[0,1]
	v_pk_add_f32 v[30:31], v[30:31], v[2:3] op_sel_hi:[1,0] neg_lo:[0,1] neg_hi:[0,1]
	v_pk_fma_f32 v[34:35], v[6:7], v[22:23], v[14:15]
	v_and_b32_e32 v23, 0xffff0000, v25
	v_and_b32_e32 v22, 0xffff0000, v24
	v_pk_add_f32 v[22:23], v[22:23], v[2:3] op_sel_hi:[1,0] neg_lo:[0,1] neg_hi:[0,1]
	v_addc_co_u32_e32 v11, vcc, 0, v11, vcc
	v_pk_mul_f32 v[30:31], v[30:31], v[2:3] op_sel:[0,1]
	v_pk_mul_f32 v[2:3], v[22:23], v[2:3] op_sel:[0,1]
	v_mov_b64_e32 v[22:23], v[220:221]
	v_mov_b64_e32 v[24:25], v[222:223]
	v_pk_fma_f32 v[2:3], v[4:5], v[2:3], v[12:13]
	v_pk_fma_f32 v[30:31], v[18:19], v[30:31], v[20:21]
	v_bfe_u32 v0, v3, 16, 1
	v_bfe_u32 v10, v2, 16, 1
	v_bfe_u32 v11, v33, 16, 1
	v_bfe_u32 v36, v32, 16, 1
	v_add3_u32 v36, v32, v36, s87
	v_add3_u32 v11, v33, v11, s87
	v_add3_u32 v2, v2, v10, s87
	v_add3_u32 v0, v3, v0, s87
	v_bfe_u32 v3, v30, 16, 1
	v_bfe_u32 v10, v31, 16, 1
	v_bfe_u32 v32, v34, 16, 1
	v_bfe_u32 v33, v35, 16, 1
	v_add3_u32 v33, v35, v33, s87
	v_add3_u32 v32, v34, v32, s87
	v_add3_u32 v10, v31, v10, s87
	v_add3_u32 v3, v30, v3, s87
	v_lshrrev_b32_e32 v3, 16, v3
	v_lshrrev_b32_e32 v10, 16, v10
	v_lshrrev_b32_e32 v30, 16, v32
	v_lshrrev_b32_e32 v31, 16, v33
	v_and_or_b32 v33, v0, s3, v31
	v_and_or_b32 v32, v2, s3, v30
	v_and_or_b32 v31, v11, s3, v10
	v_and_or_b32 v30, v36, s3, v3
	ds_write_b128 v96, v[30:33] offset:46080
	v_add_u32_e32 v0, s2, v89
	ds_read_b64 v[2:3], v0
	s_waitcnt vmcnt(1)
	v_lshlrev_b32_e32 v11, 16, v27
	v_lshlrev_b32_e32 v10, 16, v26
	v_and_b32_e32 v27, 0xffff0000, v27
	v_and_b32_e32 v26, 0xffff0000, v26
	v_lshlrev_b32_e32 v31, 16, v29
	v_lshlrev_b32_e32 v30, 16, v28
	v_and_b32_e32 v29, 0xffff0000, v29
	v_and_b32_e32 v28, 0xffff0000, v28
	s_waitcnt lgkmcnt(0)
	v_pk_add_f32 v[10:11], v[10:11], v[2:3] op_sel_hi:[1,0] neg_lo:[0,1] neg_hi:[0,1]
	v_pk_add_f32 v[26:27], v[26:27], v[2:3] op_sel_hi:[1,0] neg_lo:[0,1] neg_hi:[0,1]
	v_pk_add_f32 v[30:31], v[30:31], v[2:3] op_sel_hi:[1,0] neg_lo:[0,1] neg_hi:[0,1]
	v_pk_add_f32 v[28:29], v[28:29], v[2:3] op_sel_hi:[1,0] neg_lo:[0,1] neg_hi:[0,1]
	v_pk_mul_f32 v[10:11], v[10:11], v[2:3] op_sel:[0,1]
	v_pk_mul_f32 v[26:27], v[26:27], v[2:3] op_sel:[0,1]
	v_pk_mul_f32 v[30:31], v[30:31], v[2:3] op_sel:[0,1]
	v_pk_mul_f32 v[2:3], v[28:29], v[2:3] op_sel:[0,1]
	v_pk_fma_f32 v[26:27], v[8:9], v[26:27], v[16:17]
	v_pk_fma_f32 v[2:3], v[4:5], v[2:3], v[12:13]
	v_pk_fma_f32 v[10:11], v[18:19], v[10:11], v[20:21]
	v_pk_fma_f32 v[30:31], v[6:7], v[30:31], v[14:15]
	v_bfe_u32 v0, v3, 16, 1
	v_bfe_u32 v28, v2, 16, 1
	v_bfe_u32 v29, v27, 16, 1
	v_bfe_u32 v32, v26, 16, 1
	v_add3_u32 v26, v26, v32, s87
	v_add3_u32 v27, v27, v29, s87
	v_add3_u32 v2, v2, v28, s87
	v_add3_u32 v0, v3, v0, s87
	v_bfe_u32 v3, v10, 16, 1
	v_bfe_u32 v28, v11, 16, 1
	v_bfe_u32 v29, v30, 16, 1
	v_bfe_u32 v32, v31, 16, 1
	v_add3_u32 v31, v31, v32, s87
	v_add3_u32 v29, v30, v29, s87
	v_add3_u32 v11, v11, v28, s87
	v_add3_u32 v3, v10, v3, s87
	v_lshrrev_b32_e32 v3, 16, v3
	v_lshrrev_b32_e32 v10, 16, v11
	v_lshrrev_b32_e32 v11, 16, v29
	v_lshrrev_b32_e32 v28, 16, v31
	v_and_or_b32 v29, v0, s3, v28
	v_and_or_b32 v28, v2, s3, v11
	v_and_or_b32 v27, v27, s3, v10
	v_and_or_b32 v26, v26, s3, v3
	ds_write_b128 v96, v[26:29] offset:55296
	v_add_u32_e32 v0, s2, v90
	ds_read_b64 v[2:3], v0
	s_movk_i32 s2, 0xff00
	s_waitcnt vmcnt(0)
	v_lshlrev_b32_e32 v11, 16, v23
	v_lshlrev_b32_e32 v10, 16, v22
	s_waitcnt lgkmcnt(0)
	v_pk_add_f32 v[10:11], v[10:11], v[2:3] op_sel_hi:[1,0] neg_lo:[0,1] neg_hi:[0,1]
	s_nop 0
	v_pk_mul_f32 v[10:11], v[10:11], v[2:3] op_sel:[0,1]
	s_nop 0
	v_pk_fma_f32 v[10:11], v[18:19], v[10:11], v[20:21]
	v_and_b32_e32 v19, 0xffff0000, v23
	v_and_b32_e32 v18, 0xffff0000, v22
	v_pk_add_f32 v[18:19], v[18:19], v[2:3] op_sel_hi:[1,0] neg_lo:[0,1] neg_hi:[0,1]
	s_nop 0
	v_pk_mul_f32 v[18:19], v[18:19], v[2:3] op_sel:[0,1]
	s_nop 0
	v_pk_fma_f32 v[8:9], v[8:9], v[18:19], v[16:17]
	v_lshlrev_b32_e32 v17, 16, v25
	v_lshlrev_b32_e32 v16, 16, v24
	v_pk_add_f32 v[16:17], v[16:17], v[2:3] op_sel_hi:[1,0] neg_lo:[0,1] neg_hi:[0,1]
	s_nop 0
	v_pk_mul_f32 v[16:17], v[16:17], v[2:3] op_sel:[0,1]
	s_nop 0
	v_pk_fma_f32 v[6:7], v[6:7], v[16:17], v[14:15]
	v_and_b32_e32 v15, 0xffff0000, v25
	v_and_b32_e32 v14, 0xffff0000, v24
	v_pk_add_f32 v[14:15], v[14:15], v[2:3] op_sel_hi:[1,0] neg_lo:[0,1] neg_hi:[0,1]
	s_nop 0
	v_pk_mul_f32 v[2:3], v[14:15], v[2:3] op_sel:[0,1]
	s_nop 0
	v_pk_fma_f32 v[2:3], v[4:5], v[2:3], v[12:13]
	v_bfe_u32 v5, v9, 16, 1
	v_bfe_u32 v0, v3, 16, 1
	v_bfe_u32 v4, v2, 16, 1
	v_bfe_u32 v12, v8, 16, 1
	v_add3_u32 v8, v8, v12, s87
	v_add3_u32 v9, v9, v5, s87
	v_add3_u32 v2, v2, v4, s87
	v_add3_u32 v0, v3, v0, s87
	v_bfe_u32 v3, v10, 16, 1
	v_bfe_u32 v4, v11, 16, 1
	v_bfe_u32 v5, v6, 16, 1
	v_bfe_u32 v12, v7, 16, 1
	v_add3_u32 v7, v7, v12, s87
	v_add3_u32 v5, v6, v5, s87
	v_add3_u32 v4, v11, v4, s87
	v_add3_u32 v3, v10, v3, s87
	v_lshrrev_b32_e32 v6, 16, v3
	v_lshrrev_b32_e32 v3, 16, v4
	v_lshrrev_b32_e32 v4, 16, v5
	v_lshrrev_b32_e32 v5, 16, v7
	v_and_or_b32 v5, v0, s3, v5
	v_and_or_b32 v4, v2, s3, v4
	v_and_or_b32 v3, v9, s3, v3
	v_and_or_b32 v2, v8, s3, v6
	ds_write_b128 v96, v[2:5] offset:64512
	v_mov_b32_e32 v2, 0
	v_mov_b32_e32 v0, v95
	v_mov_b32_e32 v3, v2
	v_mov_b32_e32 v4, v2
	v_mov_b32_e32 v5, v2
	v_mov_b32_e32 v6, v2
	v_mov_b32_e32 v7, v2
	v_mov_b32_e32 v8, v2
	v_mov_b32_e32 v9, v2
	v_mov_b32_e32 v10, v2
	v_mov_b32_e32 v11, v2
	v_mov_b32_e32 v12, v2
	v_mov_b32_e32 v13, v2
	v_mov_b32_e32 v14, v2
	v_mov_b32_e32 v15, v2
	v_mov_b32_e32 v16, v2
	v_mov_b32_e32 v17, v2
	v_mov_b32_e32 v18, v2
	v_mov_b32_e32 v19, v2
	v_mov_b32_e32 v20, v2
	v_mov_b32_e32 v21, v2
	v_mov_b32_e32 v22, v2
	v_mov_b32_e32 v23, v2
	v_mov_b32_e32 v24, v2
	v_mov_b32_e32 v25, v2
	v_mov_b32_e32 v26, v2
	v_mov_b32_e32 v27, v2
	v_mov_b32_e32 v28, v2
	v_mov_b32_e32 v29, v2
	v_mov_b32_e32 v30, v2
	v_mov_b32_e32 v31, v2
	v_mov_b32_e32 v32, v2
	v_mov_b32_e32 v33, v2
	v_mov_b32_e32 v34, v2
	v_mov_b32_e32 v35, v2
	v_mov_b32_e32 v36, v2
	v_mov_b32_e32 v37, v2
	v_mov_b32_e32 v38, v2
	v_mov_b32_e32 v39, v2
	v_mov_b32_e32 v40, v2
	v_mov_b32_e32 v41, v2
	v_mov_b32_e32 v42, v2
	v_mov_b32_e32 v43, v2
	v_mov_b32_e32 v44, v2
	v_mov_b32_e32 v45, v2
	v_mov_b32_e32 v46, v2
	v_mov_b32_e32 v47, v2
	v_mov_b32_e32 v48, v2
	v_mov_b32_e32 v49, v2
	v_mov_b32_e32 v50, v2
	v_mov_b32_e32 v51, v2
	v_mov_b32_e32 v52, v2
	v_mov_b32_e32 v53, v2
	v_mov_b32_e32 v54, v2
	v_mov_b32_e32 v55, v2
	v_mov_b32_e32 v56, v2
	v_mov_b32_e32 v57, v2
	v_mov_b32_e32 v58, v2
	v_mov_b32_e32 v59, v2
	v_mov_b32_e32 v60, v2
	v_mov_b32_e32 v61, v2
	v_mov_b32_e32 v62, v2
	v_mov_b32_e32 v63, v2
	v_mov_b32_e32 v64, v2
	v_mov_b32_e32 v65, v2
	s_lshl_b32 s80, s1, 1
	v_readlane_b32 s66, v249, 27
	v_readlane_b32 s67, v249, 28
	v_lshl_add_u64 v[196:197], v[66:67], 0, s[80:81]
	v_lshlrev_b32_e32 v198, 2, v79
	v_lshl_or_b32 v198, s13, 9, v198
	v_or_b32_e32 v200, s0, v79
	v_ashrrev_i32_e32 v201, 31, v200
	v_lshlrev_b64 v[200:201], 13, v[200:201]
	v_lshl_add_u64 v[200:201], v[196:197], 0, v[200:201]
	global_load_dwordx2 v[160:161], v[200:201], off
	global_load_dwordx2 v[162:163], v[200:201], off offset:16
	global_load_dwordx2 v[164:165], v[200:201], off offset:32
	global_load_dwordx2 v[166:167], v[200:201], off offset:48
	global_load_dword v192, v198, s[66:67]
	v_or_b32_e32 v200, s0, v91
	v_ashrrev_i32_e32 v201, 31, v200
	v_lshlrev_b64 v[200:201], 13, v[200:201]
	v_lshl_add_u64 v[200:201], v[196:197], 0, v[200:201]
	global_load_dwordx2 v[168:169], v[200:201], off
	global_load_dwordx2 v[170:171], v[200:201], off offset:16
	global_load_dwordx2 v[172:173], v[200:201], off offset:32
	global_load_dwordx2 v[174:175], v[200:201], off offset:48
	global_load_dword v193, v198, s[66:67] offset:128
	v_or_b32_e32 v200, s0, v92
	v_ashrrev_i32_e32 v201, 31, v200
	v_lshlrev_b64 v[200:201], 13, v[200:201]
	v_lshl_add_u64 v[200:201], v[196:197], 0, v[200:201]
	global_load_dwordx2 v[176:177], v[200:201], off
	global_load_dwordx2 v[178:179], v[200:201], off offset:16
	global_load_dwordx2 v[180:181], v[200:201], off offset:32
	global_load_dwordx2 v[182:183], v[200:201], off offset:48
	global_load_dword v194, v198, s[66:67] offset:256
	v_or_b32_e32 v200, s0, v93
	v_ashrrev_i32_e32 v201, 31, v200
	v_lshlrev_b64 v[200:201], 13, v[200:201]
	v_lshl_add_u64 v[200:201], v[196:197], 0, v[200:201]
	global_load_dwordx2 v[184:185], v[200:201], off
	global_load_dwordx2 v[186:187], v[200:201], off offset:16
	global_load_dwordx2 v[188:189], v[200:201], off offset:32
	global_load_dwordx2 v[190:191], v[200:201], off offset:48
	global_load_dword v195, v198, s[66:67] offset:384
	s_waitcnt lgkmcnt(0)
	s_barrier

.LBB0_435:
	v_ashrrev_i32_e32 v15, 4, v14
	v_add_u32_e32 v8, s2, v15
	v_ashrrev_i32_e32 v9, 31, v8
	v_and_b32_e32 v0, 60, v7
	v_lshlrev_b64 v[2:3], 14, v[8:9]
	v_lshl_add_u64 v[2:3], s[8:9], 0, v[2:3]
	v_lshlrev_b32_e32 v0, 2, v0
	v_lshl_add_u64 v[2:3], v[2:3], 0, v[0:1]
	global_load_dwordx4 v[2:5], v[2:3], off
	v_add_u32_e32 v174, 0x200, v14
	v_add_u32_e32 v167, 0x800, v7
	v_mov_b32_e32 v161, 0
	v_ashrrev_i32_e32 v175, 4, v174
	v_add_u32_e32 v168, s2, v175
	v_ashrrev_i32_e32 v169, 31, v168
	v_and_b32_e32 v160, 60, v167
	v_lshlrev_b64 v[162:163], 14, v[168:169]
	v_lshl_add_u64 v[162:163], s[8:9], 0, v[162:163]
	v_lshlrev_b32_e32 v160, 2, v160
	v_lshl_add_u64 v[162:163], v[162:163], 0, v[160:161]
	global_load_dwordx4 v[162:165], v[162:163], off
	s_andn2_b64 vcc, exec, s[84:85]
	s_cbranch_vccz .Lcv_g433
	v_mov_b32_e32 v8, 1.0
	v_mov_b32_e32 v168, 1.0
	s_branch .Lcv_w433
.Lcv_g433:
	v_lshl_add_u64 v[8:9], v[8:9], 2, s[44:45]
	global_load_dword v8, v[8:9], off
	v_lshl_add_u64 v[168:169], v[168:169], 2, s[44:45]
	global_load_dword v168, v[168:169], off
.Lcv_w433:
	v_mul_lo_u32 v9, v15, s27
	v_add3_u32 v0, 0, v9, v0
	v_mul_lo_u32 v169, v175, s27
	v_add3_u32 v160, 0, v169, v160
	s_waitcnt vmcnt(0)
	v_pk_mul_f32 v[2:3], v[2:3], v[8:9] op_sel_hi:[1,0]
	ds_write2_b32 v0, v2, v3 offset1:1
	v_pk_mul_f32 v[2:3], v[4:5], v[8:9] op_sel_hi:[1,0]
	ds_write2_b32 v0, v2, v3 offset0:2 offset1:3
	v_pk_mul_f32 v[162:163], v[162:163], v[168:169] op_sel_hi:[1,0]
	ds_write2_b32 v160, v162, v163 offset1:1
	v_pk_mul_f32 v[162:163], v[164:165], v[168:169] op_sel_hi:[1,0]
	ds_write2_b32 v160, v162, v163 offset0:2 offset1:3
	s_branch .LBB0_430

.LBB0_444:
	v_ashrrev_i32_e32 v15, 4, v14
	v_add_u32_e32 v8, s2, v15
	v_ashrrev_i32_e32 v9, 31, v8
	v_and_b32_e32 v0, 60, v7
	v_lshlrev_b64 v[2:3], 14, v[8:9]
	v_lshl_add_u64 v[2:3], s[10:11], 0, v[2:3]
	v_lshlrev_b32_e32 v0, 2, v0
	v_lshl_add_u64 v[2:3], v[2:3], 0, v[0:1]
	global_load_dwordx4 v[2:5], v[2:3], off
	v_add_u32_e32 v174, 0x200, v14
	v_add_u32_e32 v167, 0x800, v7
	v_mov_b32_e32 v161, 0
	v_ashrrev_i32_e32 v175, 4, v174
	v_add_u32_e32 v168, s2, v175
	v_ashrrev_i32_e32 v169, 31, v168
	v_and_b32_e32 v160, 60, v167
	v_lshlrev_b64 v[162:163], 14, v[168:169]
	v_lshl_add_u64 v[162:163], s[10:11], 0, v[162:163]
	v_lshlrev_b32_e32 v160, 2, v160
	v_lshl_add_u64 v[162:163], v[162:163], 0, v[160:161]
	global_load_dwordx4 v[162:165], v[162:163], off
	s_andn2_b64 vcc, exec, s[84:85]
	s_cbranch_vccz .Lcv_g442
	v_mov_b32_e32 v8, 1.0
	v_mov_b32_e32 v168, 1.0
	s_branch .Lcv_w442
.Lcv_g442:
	v_readlane_b32 s16, v250, 46
	v_readlane_b32 s17, v250, 47
	s_nop 1
	v_lshl_add_u64 v[8:9], v[8:9], 2, s[16:17]
	global_load_dword v8, v[8:9], off
	v_lshl_add_u64 v[168:169], v[168:169], 2, s[16:17]
	global_load_dword v168, v[168:169], off

.Lcv_g451:
	v_readlane_b32 s16, v250, 52
	v_readlane_b32 s17, v250, 53
	s_nop 1
	v_lshl_add_u64 v[8:9], v[8:9], 2, s[16:17]
	global_load_dword v8, v[8:9], off
	v_lshl_add_u64 v[168:169], v[168:169], 2, s[16:17]
	global_load_dword v168, v[168:169], off

.Lcv_g460:
	v_readlane_b32 s16, v250, 58
	v_readlane_b32 s17, v250, 59
	s_nop 1
	v_lshl_add_u64 v[8:9], v[8:9], 2, s[16:17]
	global_load_dword v8, v[8:9], off
	v_lshl_add_u64 v[168:169], v[168:169], 2, s[16:17]
	global_load_dword v168, v[168:169], off

.LBB0_495:
	v_ashrrev_i32_e32 v15, 4, v14
	v_and_b32_e32 v0, 60, v7
	v_add_u32_e32 v8, s2, v15
	v_mov_b64_e32 v[2:3], s[10:11]
	v_mad_i64_i32 v[2:3], s[16:17], v8, s18, v[2:3]
	v_lshlrev_b32_e32 v0, 2, v0
	v_lshl_add_u64 v[2:3], v[2:3], 0, v[0:1]
	global_load_dwordx4 v[2:5], v[2:3], off
	v_add_u32_e32 v174, 0x200, v14
	v_add_u32_e32 v167, 0x800, v7
	v_mov_b32_e32 v161, 0
	v_ashrrev_i32_e32 v175, 4, v174
	v_and_b32_e32 v160, 60, v167
	v_add_u32_e32 v168, s2, v175
	v_mov_b64_e32 v[162:163], s[10:11]
	v_mad_i64_i32 v[162:163], s[16:17], v168, s18, v[162:163]
	v_lshlrev_b32_e32 v160, 2, v160
	v_lshl_add_u64 v[162:163], v[162:163], 0, v[160:161]
	global_load_dwordx4 v[162:165], v[162:163], off
	s_andn2_b64 vcc, exec, s[88:89]
	s_cbranch_vccz .Lcv_g493
	v_mov_b32_e32 v8, 1.0
	v_mov_b32_e32 v168, 1.0
	s_branch .Lcv_w493
.Lcv_g493:
	v_ashrrev_i32_e32 v9, 31, v8
	v_lshl_add_u64 v[8:9], v[8:9], 2, s[42:43]
	global_load_dword v8, v[8:9], off
	v_ashrrev_i32_e32 v169, 31, v168
	v_lshl_add_u64 v[168:169], v[168:169], 2, s[42:43]
	global_load_dword v168, v[168:169], off

.LBB0_504:
	v_ashrrev_i32_e32 v15, 4, v14
	v_and_b32_e32 v0, 60, v7
	v_add_u32_e32 v8, s2, v15
	v_mov_b64_e32 v[2:3], s[8:9]
	v_mad_i64_i32 v[2:3], s[14:15], v8, s18, v[2:3]
	v_lshlrev_b32_e32 v0, 2, v0
	v_lshl_add_u64 v[2:3], v[2:3], 0, v[0:1]
	global_load_dwordx4 v[2:5], v[2:3], off
	v_add_u32_e32 v174, 0x200, v14
	v_add_u32_e32 v167, 0x800, v7
	v_mov_b32_e32 v161, 0
	v_ashrrev_i32_e32 v175, 4, v174
	v_and_b32_e32 v160, 60, v167
	v_add_u32_e32 v168, s2, v175
	v_mov_b64_e32 v[162:163], s[8:9]
	v_mad_i64_i32 v[162:163], s[14:15], v168, s18, v[162:163]
	v_lshlrev_b32_e32 v160, 2, v160
	v_lshl_add_u64 v[162:163], v[162:163], 0, v[160:161]
	global_load_dwordx4 v[162:165], v[162:163], off
	s_andn2_b64 vcc, exec, s[88:89]
	s_cbranch_vccz .Lcv_g502
	v_mov_b32_e32 v8, 1.0
	v_mov_b32_e32 v168, 1.0
	s_branch .Lcv_w502
.Lcv_g502:
	v_ashrrev_i32_e32 v9, 31, v8
	v_lshl_add_u64 v[8:9], v[8:9], 2, s[74:75]
	global_load_dword v8, v[8:9], off
	v_ashrrev_i32_e32 v169, 31, v168
	v_lshl_add_u64 v[168:169], v[168:169], 2, s[74:75]
	global_load_dword v168, v[168:169], off
